# P8 fused epilogue: partial-sum exchange by polling the (zero-initialised) partials instead of a flag, gain loads issued early
# baseline (speedup 1.0000x reference)
;     __device__ __forceinline__ Pre pre4(int row, int col) const { const size_t o = (size_t)row * DM + col; Pre p; p.g = NTL((const v2u*)(SG + o)); p.m = (v2u){0u, 0u}; if (MODE == 1) p.m = NTL((const v2u*)(MG + o)); return p; }
;     __device__ __forceinline__ Pre pre4(int row, int col) const { const float* sb = (row < TP) ? srcP : srcS - (size_t)TP * DM; Pre p; p.s = NTL((const f32x4*)(sb + (size_t)row * DM + col)); return p; }
;     __device__ __forceinline__ float store4pg(int row, int col, f32x4 a, const Pre& p, f32x4 gg) const {
;         const size_t o = (size_t)row * DM + col; const f32x4 v = p.s + a * alpha; *(f32x4*)(out + o) = v;
;     __device__ __forceinline__ void operator()(const f32x4 (&acc)[2][2][4][2], const Unit& u, int wr, int wc, int fr, int fq) const {
;     ...
;         for (int am = 0; am < 4; ++am) {
;             const int ai = am >> 1, mb = (am & 1) * 2;
;             Pre pv[2][2][2];
; #pragma unroll
;             for (int mm = 0; mm < 2; ++mm)
; #pragma unroll
;                 for (int bj = 0; bj < 2; ++bj)
; #pragma unroll
;                     for (int n = 0; n < 2; ++n) pv[mm][bj][n] = pre4(row0 + ai * HALF + (mb + mm) * 16, col0 + bj * HALF + n * 16);
; #pragma unroll
;             for (int mm = 0; mm < 2; ++mm) { const int m = mb + mm; float ss = 0.f;
; #pragma unroll
;                 for (int bj = 0; bj < 2; ++bj)
; #pragma unroll
;                     for (int n = 0; n < 2; ++n) ss += store4pg(row0 + ai * HALF + m * 16, col0 + bj * HALF + n * 16, acc[ai][bj][m][n], pv[mm][bj][n], gg[bj][n]);
.LBB0_1901:
	s_lshl_b32 s100, s64, 20
	s_lshl_b32 s101, s65, 10
	s_add_u32 s98, s20, s100
	s_addc_u32 s99, s21, 0
	s_add_u32 s98, s98, s101
	s_addc_u32 s99, s99, 0
	v_lshlrev_b32_e32 v142, 12, v144
	v_lshl_add_u32 v142, v146, 2, v142
	v_mov_b32_e32 v143, v142
	global_load_dwordx4 v[170:173], v143, s[98:99]
	global_load_dwordx4 v[174:177], v143, s[98:99] offset:64
	global_load_dwordx4 v[178:181], v143, s[98:99] offset:512
	global_load_dwordx4 v[182:185], v143, s[98:99] offset:576
	v_add_u32_e32 v143, 0x10000, v142
	global_load_dwordx4 v[186:189], v143, s[98:99]
	global_load_dwordx4 v[190:193], v143, s[98:99] offset:64
	global_load_dwordx4 v[194:197], v143, s[98:99] offset:512
	global_load_dwordx4 v[198:201], v143, s[98:99] offset:576
	v_add_u32_e32 v143, 0x20000, v142
	global_load_dwordx4 v[202:205], v143, s[98:99]
	global_load_dwordx4 v[206:209], v143, s[98:99] offset:64
	global_load_dwordx4 v[210:213], v143, s[98:99] offset:512
	global_load_dwordx4 v[214:217], v143, s[98:99] offset:576
	v_add_u32_e32 v143, 0x30000, v142
	global_load_dwordx4 v[218:221], v143, s[98:99]
	global_load_dwordx4 v[222:225], v143, s[98:99] offset:64
	global_load_dwordx4 v[226:229], v143, s[98:99] offset:512
	global_load_dwordx4 v[230:233], v143, s[98:99] offset:576
	s_waitcnt vmcnt(8)
	v_pk_fma_f32 v[126:127], v[126:127], 0.5, v[170:171] op_sel_hi:[1,0,1]
	v_pk_fma_f32 v[128:129], v[128:129], 0.5, v[172:173] op_sel_hi:[1,0,1]
	v_pk_fma_f32 v[122:123], v[122:123], 0.5, v[174:175] op_sel_hi:[1,0,1]
	v_pk_fma_f32 v[124:125], v[124:125], 0.5, v[176:177] op_sel_hi:[1,0,1]
	v_pk_fma_f32 v[110:111], v[110:111], 0.5, v[178:179] op_sel_hi:[1,0,1]
	v_pk_fma_f32 v[112:113], v[112:113], 0.5, v[180:181] op_sel_hi:[1,0,1]
	v_pk_fma_f32 v[106:107], v[106:107], 0.5, v[182:183] op_sel_hi:[1,0,1]
	v_pk_fma_f32 v[108:109], v[108:109], 0.5, v[184:185] op_sel_hi:[1,0,1]
	v_pk_fma_f32 v[118:119], v[118:119], 0.5, v[186:187] op_sel_hi:[1,0,1]
	v_pk_fma_f32 v[120:121], v[120:121], 0.5, v[188:189] op_sel_hi:[1,0,1]
	v_pk_fma_f32 v[114:115], v[114:115], 0.5, v[190:191] op_sel_hi:[1,0,1]
	v_pk_fma_f32 v[116:117], v[116:117], 0.5, v[192:193] op_sel_hi:[1,0,1]
	v_pk_fma_f32 v[102:103], v[102:103], 0.5, v[194:195] op_sel_hi:[1,0,1]
	v_pk_fma_f32 v[104:105], v[104:105], 0.5, v[196:197] op_sel_hi:[1,0,1]
	v_pk_fma_f32 v[98:99], v[98:99], 0.5, v[198:199] op_sel_hi:[1,0,1]
	v_pk_fma_f32 v[100:101], v[100:101], 0.5, v[200:201] op_sel_hi:[1,0,1]
	v_add_u32_e32 v143, 0x80000, v142
	global_load_dwordx4 v[170:173], v143, s[98:99]
	global_load_dwordx4 v[174:177], v143, s[98:99] offset:64
	global_load_dwordx4 v[178:181], v143, s[98:99] offset:512
	global_load_dwordx4 v[182:185], v143, s[98:99] offset:576
	v_add_u32_e32 v143, 0x90000, v142
	global_load_dwordx4 v[186:189], v143, s[98:99]
	global_load_dwordx4 v[190:193], v143, s[98:99] offset:64
	global_load_dwordx4 v[194:197], v143, s[98:99] offset:512
	global_load_dwordx4 v[198:201], v143, s[98:99] offset:576
	s_waitcnt vmcnt(8)
	v_pk_fma_f32 v[94:95], v[94:95], 0.5, v[202:203] op_sel_hi:[1,0,1]
	v_pk_fma_f32 v[96:97], v[96:97], 0.5, v[204:205] op_sel_hi:[1,0,1]
	v_pk_fma_f32 v[90:91], v[90:91], 0.5, v[206:207] op_sel_hi:[1,0,1]
	v_pk_fma_f32 v[92:93], v[92:93], 0.5, v[208:209] op_sel_hi:[1,0,1]
	v_pk_fma_f32 v[78:79], v[78:79], 0.5, v[210:211] op_sel_hi:[1,0,1]
	v_pk_fma_f32 v[80:81], v[80:81], 0.5, v[212:213] op_sel_hi:[1,0,1]
	v_pk_fma_f32 v[74:75], v[74:75], 0.5, v[214:215] op_sel_hi:[1,0,1]
	v_pk_fma_f32 v[76:77], v[76:77], 0.5, v[216:217] op_sel_hi:[1,0,1]
	v_pk_fma_f32 v[86:87], v[86:87], 0.5, v[218:219] op_sel_hi:[1,0,1]
	v_pk_fma_f32 v[88:89], v[88:89], 0.5, v[220:221] op_sel_hi:[1,0,1]
	v_pk_fma_f32 v[82:83], v[82:83], 0.5, v[222:223] op_sel_hi:[1,0,1]
	v_pk_fma_f32 v[84:85], v[84:85], 0.5, v[224:225] op_sel_hi:[1,0,1]
	v_pk_fma_f32 v[70:71], v[70:71], 0.5, v[226:227] op_sel_hi:[1,0,1]
	v_pk_fma_f32 v[72:73], v[72:73], 0.5, v[228:229] op_sel_hi:[1,0,1]
	v_pk_fma_f32 v[66:67], v[66:67], 0.5, v[230:231] op_sel_hi:[1,0,1]
	v_pk_fma_f32 v[68:69], v[68:69], 0.5, v[232:233] op_sel_hi:[1,0,1]
	v_add_u32_e32 v143, 0xa0000, v142
	global_load_dwordx4 v[202:205], v143, s[98:99]
	global_load_dwordx4 v[206:209], v143, s[98:99] offset:64
	global_load_dwordx4 v[210:213], v143, s[98:99] offset:512
	global_load_dwordx4 v[214:217], v143, s[98:99] offset:576
	v_add_u32_e32 v143, 0xb0000, v142
	global_load_dwordx4 v[218:221], v143, s[98:99]
	global_load_dwordx4 v[222:225], v143, s[98:99] offset:64
	global_load_dwordx4 v[226:229], v143, s[98:99] offset:512
	global_load_dwordx4 v[230:233], v143, s[98:99] offset:576
	s_waitcnt vmcnt(8)
	v_pk_fma_f32 v[62:63], v[62:63], 0.5, v[170:171] op_sel_hi:[1,0,1]
	v_pk_fma_f32 v[64:65], v[64:65], 0.5, v[172:173] op_sel_hi:[1,0,1]
	v_pk_fma_f32 v[58:59], v[58:59], 0.5, v[174:175] op_sel_hi:[1,0,1]
	v_pk_fma_f32 v[60:61], v[60:61], 0.5, v[176:177] op_sel_hi:[1,0,1]
	v_pk_fma_f32 v[46:47], v[46:47], 0.5, v[178:179] op_sel_hi:[1,0,1]
	v_pk_fma_f32 v[48:49], v[48:49], 0.5, v[180:181] op_sel_hi:[1,0,1]
	v_pk_fma_f32 v[42:43], v[42:43], 0.5, v[182:183] op_sel_hi:[1,0,1]
	v_pk_fma_f32 v[44:45], v[44:45], 0.5, v[184:185] op_sel_hi:[1,0,1]
	v_pk_fma_f32 v[54:55], v[54:55], 0.5, v[186:187] op_sel_hi:[1,0,1]
	v_pk_fma_f32 v[56:57], v[56:57], 0.5, v[188:189] op_sel_hi:[1,0,1]
	v_pk_fma_f32 v[50:51], v[50:51], 0.5, v[190:191] op_sel_hi:[1,0,1]
	v_pk_fma_f32 v[52:53], v[52:53], 0.5, v[192:193] op_sel_hi:[1,0,1]
	v_pk_fma_f32 v[38:39], v[38:39], 0.5, v[194:195] op_sel_hi:[1,0,1]
	v_pk_fma_f32 v[40:41], v[40:41], 0.5, v[196:197] op_sel_hi:[1,0,1]
	v_pk_fma_f32 v[34:35], v[34:35], 0.5, v[198:199] op_sel_hi:[1,0,1]
	v_pk_fma_f32 v[36:37], v[36:37], 0.5, v[200:201] op_sel_hi:[1,0,1]
	s_waitcnt vmcnt(0)
; __device__ __forceinline__ unsigned pk2(float lo, float hi) { const f32x2_t_ v = {lo, hi}; return __builtin_bit_cast(unsigned, __builtin_convertvector(v, bf16x2_t_)); }
;     __device__ __forceinline__ float store4pg(int row, int col, f32x4 a, const Pre& p, f32x4 gg) const {
;         const size_t o = (size_t)row * DM + col; const f32x4 v = p.s + a * alpha; *(f32x4*)(out + o) = v;
;         if (XNo) { v2u w; w.x = pk2(v[0] * gg[0], v[1] * gg[1]); w.y = pk2(v[2] * gg[2], v[3] * gg[3]); *(v2u*)(XNo + o) = w; return (v[0] * v[0] + v[1] * v[1]) + (v[2] * v[2] + v[3] * v[3]); }
;     __device__ __forceinline__ void operator()(const f32x4 (&acc)[2][2][4][2], const Unit& u, int wr, int wc, int fr, int fq) const {
;     ...
;             for (int mm = 0; mm < 2; ++mm) { const int m = mb + mm; float ss = 0.f;
; #pragma unroll
;                 for (int bj = 0; bj < 2; ++bj)
; #pragma unroll
;                     for (int n = 0; n < 2; ++n) ss += store4pg(row0 + ai * HALF + m * 16, col0 + bj * HALF + n * 16, acc[ai][bj][m][n], pv[mm][bj][n], gg[bj][n]);
;                 if (norm) { ss += __shfl_xor(ss, 16); ss += __shfl_xor(ss, 32); if (fq == 0) (void)__hip_atomic_fetch_add(ROWSUM + ai * HALF + wr * 64 + m * 16 + fr, ss, __ATOMIC_RELAXED, __HIP_MEMORY_SCOPE_WORKGROUP); } }
;         }
;         if (norm) { asm volatile("s_waitcnt lgkmcnt(0)" ::: "memory"); __builtin_amdgcn_s_barrier(); asm volatile("" ::: "memory");
;             if (threadIdx.x < 256) PP[(size_t)(u.pm * BM + threadIdx.x) * 4 + u.pn] = ROWSUM[threadIdx.x]; }
	v_pk_fma_f32 v[30:31], v[30:31], 0.5, v[202:203] op_sel_hi:[1,0,1]
	v_pk_fma_f32 v[32:33], v[32:33], 0.5, v[204:205] op_sel_hi:[1,0,1]
	v_pk_fma_f32 v[26:27], v[26:27], 0.5, v[206:207] op_sel_hi:[1,0,1]
	v_pk_fma_f32 v[28:29], v[28:29], 0.5, v[208:209] op_sel_hi:[1,0,1]
	v_pk_fma_f32 v[18:19], v[18:19], 0.5, v[210:211] op_sel_hi:[1,0,1]
	v_pk_fma_f32 v[20:21], v[20:21], 0.5, v[212:213] op_sel_hi:[1,0,1]
	v_pk_fma_f32 v[10:11], v[10:11], 0.5, v[214:215] op_sel_hi:[1,0,1]
	v_pk_fma_f32 v[12:13], v[12:13], 0.5, v[216:217] op_sel_hi:[1,0,1]
	v_pk_fma_f32 v[22:23], v[22:23], 0.5, v[218:219] op_sel_hi:[1,0,1]
	v_pk_fma_f32 v[24:25], v[24:25], 0.5, v[220:221] op_sel_hi:[1,0,1]
	v_pk_fma_f32 v[14:15], v[14:15], 0.5, v[222:223] op_sel_hi:[1,0,1]
	v_pk_fma_f32 v[16:17], v[16:17], 0.5, v[224:225] op_sel_hi:[1,0,1]
	v_pk_fma_f32 v[6:7], v[6:7], 0.5, v[226:227] op_sel_hi:[1,0,1]
	v_pk_fma_f32 v[8:9], v[8:9], 0.5, v[228:229] op_sel_hi:[1,0,1]
	v_pk_fma_f32 v[2:3], v[2:3], 0.5, v[230:231] op_sel_hi:[1,0,1]
	v_pk_fma_f32 v[4:5], v[4:5], 0.5, v[232:233] op_sel_hi:[1,0,1]
	s_load_dwordx2 s[100:101], s[0:1], 0xa0
	v_lshlrev_b32_e32 v198, 2, v146
	s_lshl_b32 s98, s65, 10
	v_add_u32_e32 v198, s98, v198
	s_waitcnt lgkmcnt(0)
	global_load_dwordx4 v[202:205], v198, s[100:101]
	global_load_dwordx4 v[206:209], v198, s[100:101] offset:64
	global_load_dwordx4 v[210:213], v198, s[100:101] offset:512
	global_load_dwordx4 v[214:217], v198, s[100:101] offset:576
	v_pk_mul_f32 v[178:179], v[126:127], v[126:127]
	v_pk_fma_f32 v[178:179], v[128:129], v[128:129], v[178:179]
	v_pk_fma_f32 v[178:179], v[122:123], v[122:123], v[178:179]
	v_pk_fma_f32 v[178:179], v[124:125], v[124:125], v[178:179]
	v_pk_fma_f32 v[178:179], v[110:111], v[110:111], v[178:179]
	v_pk_fma_f32 v[178:179], v[112:113], v[112:113], v[178:179]
	v_pk_fma_f32 v[178:179], v[106:107], v[106:107], v[178:179]
	v_pk_fma_f32 v[178:179], v[108:109], v[108:109], v[178:179]
	v_add_f32_e32 v170, v178, v179
	v_pk_mul_f32 v[178:179], v[118:119], v[118:119]
	v_pk_fma_f32 v[178:179], v[120:121], v[120:121], v[178:179]
	v_pk_fma_f32 v[178:179], v[114:115], v[114:115], v[178:179]
	v_pk_fma_f32 v[178:179], v[116:117], v[116:117], v[178:179]
	v_pk_fma_f32 v[178:179], v[102:103], v[102:103], v[178:179]
	v_pk_fma_f32 v[178:179], v[104:105], v[104:105], v[178:179]
	v_pk_fma_f32 v[178:179], v[98:99], v[98:99], v[178:179]
	v_pk_fma_f32 v[178:179], v[100:101], v[100:101], v[178:179]
	v_add_f32_e32 v171, v178, v179
	v_pk_mul_f32 v[178:179], v[94:95], v[94:95]
	v_pk_fma_f32 v[178:179], v[96:97], v[96:97], v[178:179]
	v_pk_fma_f32 v[178:179], v[90:91], v[90:91], v[178:179]
	v_pk_fma_f32 v[178:179], v[92:93], v[92:93], v[178:179]
	v_pk_fma_f32 v[178:179], v[78:79], v[78:79], v[178:179]
	v_pk_fma_f32 v[178:179], v[80:81], v[80:81], v[178:179]
	v_pk_fma_f32 v[178:179], v[74:75], v[74:75], v[178:179]
	v_pk_fma_f32 v[178:179], v[76:77], v[76:77], v[178:179]
	v_add_f32_e32 v172, v178, v179
	v_pk_mul_f32 v[178:179], v[86:87], v[86:87]
	v_pk_fma_f32 v[178:179], v[88:89], v[88:89], v[178:179]
	v_pk_fma_f32 v[178:179], v[82:83], v[82:83], v[178:179]
	v_pk_fma_f32 v[178:179], v[84:85], v[84:85], v[178:179]
	v_pk_fma_f32 v[178:179], v[70:71], v[70:71], v[178:179]
	v_pk_fma_f32 v[178:179], v[72:73], v[72:73], v[178:179]
	v_pk_fma_f32 v[178:179], v[66:67], v[66:67], v[178:179]
	v_pk_fma_f32 v[178:179], v[68:69], v[68:69], v[178:179]
	v_add_f32_e32 v173, v178, v179
	v_pk_mul_f32 v[178:179], v[62:63], v[62:63]
	v_pk_fma_f32 v[178:179], v[64:65], v[64:65], v[178:179]
	v_pk_fma_f32 v[178:179], v[58:59], v[58:59], v[178:179]
	v_pk_fma_f32 v[178:179], v[60:61], v[60:61], v[178:179]
	v_pk_fma_f32 v[178:179], v[46:47], v[46:47], v[178:179]
	v_pk_fma_f32 v[178:179], v[48:49], v[48:49], v[178:179]
	v_pk_fma_f32 v[178:179], v[42:43], v[42:43], v[178:179]
	v_pk_fma_f32 v[178:179], v[44:45], v[44:45], v[178:179]
	v_add_f32_e32 v174, v178, v179
	v_pk_mul_f32 v[178:179], v[54:55], v[54:55]
	v_pk_fma_f32 v[178:179], v[56:57], v[56:57], v[178:179]
	v_pk_fma_f32 v[178:179], v[50:51], v[50:51], v[178:179]
	v_pk_fma_f32 v[178:179], v[52:53], v[52:53], v[178:179]
	v_pk_fma_f32 v[178:179], v[38:39], v[38:39], v[178:179]
	v_pk_fma_f32 v[178:179], v[40:41], v[40:41], v[178:179]
	v_pk_fma_f32 v[178:179], v[34:35], v[34:35], v[178:179]
	v_pk_fma_f32 v[178:179], v[36:37], v[36:37], v[178:179]
	v_add_f32_e32 v175, v178, v179
	v_pk_mul_f32 v[178:179], v[30:31], v[30:31]
	v_pk_fma_f32 v[178:179], v[32:33], v[32:33], v[178:179]
	v_pk_fma_f32 v[178:179], v[26:27], v[26:27], v[178:179]
	v_pk_fma_f32 v[178:179], v[28:29], v[28:29], v[178:179]
	v_pk_fma_f32 v[178:179], v[18:19], v[18:19], v[178:179]
	v_pk_fma_f32 v[178:179], v[20:21], v[20:21], v[178:179]
	v_pk_fma_f32 v[178:179], v[10:11], v[10:11], v[178:179]
	v_pk_fma_f32 v[178:179], v[12:13], v[12:13], v[178:179]
	v_add_f32_e32 v176, v178, v179
	v_pk_mul_f32 v[178:179], v[22:23], v[22:23]
	v_pk_fma_f32 v[178:179], v[24:25], v[24:25], v[178:179]
	v_pk_fma_f32 v[178:179], v[14:15], v[14:15], v[178:179]
	v_pk_fma_f32 v[178:179], v[16:17], v[16:17], v[178:179]
	v_pk_fma_f32 v[178:179], v[6:7], v[6:7], v[178:179]
	v_pk_fma_f32 v[178:179], v[8:9], v[8:9], v[178:179]
	v_pk_fma_f32 v[178:179], v[2:3], v[2:3], v[178:179]
	v_pk_fma_f32 v[178:179], v[4:5], v[4:5], v[178:179]
	v_add_f32_e32 v177, v178, v179
	v_and_b32_e32 v183, 0xff, v0
	v_lshlrev_b32_e32 v184, 2, v183
	v_add_u32_e32 v182, 0x20800, v184
	v_mov_b32_e32 v185, 0
	ds_write_b32 v182, v185
	s_waitcnt lgkmcnt(0)
	s_barrier
	v_lshlrev_b32_e32 v185, 2, v144
	v_add_u32_e32 v185, 0x20800, v185
	ds_add_f32 v185, v170
	ds_add_f32 v185, v171 offset:64
	ds_add_f32 v185, v172 offset:128
	ds_add_f32 v185, v173 offset:192
	ds_add_f32 v185, v174 offset:512
	ds_add_f32 v185, v175 offset:576
	ds_add_f32 v185, v176 offset:640
	ds_add_f32 v185, v177 offset:704
	s_waitcnt lgkmcnt(0)
	s_barrier
	ds_read_b32 v185, v182
	s_lshl_b32 s100, s64, 12
	s_add_u32 s98, s22, 0x20000
	s_addc_u32 s99, s23, 0
	s_add_u32 s98, s98, s100
	s_addc_u32 s99, s99, 0
	s_lshl_b32 s101, s65, 2
	v_lshlrev_b32_e32 v184, 4, v183
	v_add_u32_e32 v199, s101, v184
	s_waitcnt lgkmcnt(0)
	global_store_dword v199, v185, s[98:99] sc0 sc1
	s_mov_b32 s100, 0
; __device__ __forceinline__ float row_rstd(const float* PP, const float* PS, int row) {
;     float ss;
;     if (row < TP) { const f32x4 a = NTL((const f32x4*)(PP + (size_t)row * 4)); ss = (a[0] + a[1]) + (a[2] + a[3]); }
;     else { const f32x4* p = (const f32x4*)(PS + (size_t)(row - TP) * 16); const f32x4 a = (NTL(p) + NTL(p + 1)) + (NTL(p + 2) + NTL(p + 3)); ss = (a[0] + a[1]) + (a[2] + a[3]); }
;     return 1.0f / sqrtf(ss * (1.0f / DM) + EPS);
;     __device__ __forceinline__ void operator()(const f32x4 (&acc)[2][2][4][2], const Unit& u, int wr, int wc, int fr, int fq) const {
;     ...
;                 if (norm) { ss += __shfl_xor(ss, 16); ss += __shfl_xor(ss, 32); if (fq == 0) (void)__hip_atomic_fetch_add(ROWSUM + ai * HALF + wr * 64 + m * 16 + fr, ss, __ATOMIC_RELAXED, __HIP_MEMORY_SCOPE_WORKGROUP); } }
;         }
;         if (norm) { asm volatile("s_waitcnt lgkmcnt(0)" ::: "memory"); __builtin_amdgcn_s_barrier(); asm volatile("" ::: "memory");
;             if (threadIdx.x < 256) PP[(size_t)(u.pm * BM + threadIdx.x) * 4 + u.pn] = ROWSUM[threadIdx.x]; }
.Lp8f_a_poll:
	global_load_dwordx4 v[186:189], v184, s[98:99] sc0 sc1
	s_waitcnt vmcnt(0)
	v_min_u32_e32 v200, v186, v187
	v_min3_u32 v200, v200, v188, v189
	v_cmp_eq_u32_e32 vcc, 0, v200
	s_cbranch_vccz .Lp8f_a_got
	s_sleep 1
	s_add_i32 s100, s100, 1
	s_cmp_lt_u32 s100, 0x4000
	s_cbranch_scc1 .Lp8f_a_poll
.Lp8f_a_got:
	v_mov_b32_e32 v190, 0x358637bd
	v_mov_b32_e32 v191, 0x260
	v_add_f32_e32 v186, v186, v187
	v_add_f32_e32 v188, v188, v189
	v_add_f32_e32 v192, v186, v188
	v_fmamk_f32 v192, v192, 0x3a800000, v190
	v_mul_f32_e32 v194, 0x4f800000, v192
	s_mov_b32 s100, 0xf800000
	v_cmp_gt_f32_e32 vcc, s100, v192
	s_nop 1
	v_cndmask_b32_e32 v192, v192, v194, vcc
	v_sqrt_f32_e32 v194, v192
	s_nop 0
	v_add_u32_e32 v195, -1, v194
	v_add_u32_e32 v196, 1, v194
	v_fma_f32 v197, -v195, v194, v192
	v_fma_f32 v198, -v196, v194, v192
	v_cmp_ge_f32_e64 s[100:101], 0, v197
	s_nop 1
	v_cndmask_b32_e64 v194, v194, v195, s[100:101]
	v_cmp_lt_f32_e64 s[100:101], 0, v198
	s_nop 1
	v_cndmask_b32_e64 v194, v194, v196, s[100:101]
	v_mul_f32_e32 v195, 0x37800000, v194
	v_cndmask_b32_e32 v194, v194, v195, vcc
	v_cmp_class_f32_e32 vcc, v192, v191
	s_nop 1
	v_cndmask_b32_e32 v192, v194, v192, vcc
	v_div_scale_f32 v194, s[100:101], v192, v192, 1.0
	v_rcp_f32_e32 v195, v194
	v_div_scale_f32 v196, vcc, 1.0, v192, 1.0
	v_fma_f32 v197, -v194, v195, 1.0
	v_fmac_f32_e32 v195, v197, v195
	v_mul_f32_e32 v197, v196, v195
	v_fma_f32 v198, -v194, v197, v196
	v_fmac_f32_e32 v197, v198, v195
	v_fma_f32 v194, -v194, v197, v196
	v_div_fmas_f32 v194, v194, v195, v197
	v_div_fixup_f32 v194, v194, v192, 1.0
	v_add_u32_e32 v182, 0x800, v182
	ds_write_b32 v182, v194
	s_waitcnt lgkmcnt(0)
	s_barrier
	v_lshlrev_b32_e32 v185, 2, v144
	v_add_u32_e32 v185, 0x21000, v185
	ds_read_b32 v218, v185
	ds_read_b32 v219, v185 offset:64
	ds_read_b32 v220, v185 offset:128
	ds_read_b32 v221, v185 offset:192
	ds_read_b32 v222, v185 offset:512
	ds_read_b32 v223, v185 offset:576
	ds_read_b32 v224, v185 offset:640
	ds_read_b32 v225, v185 offset:704
	s_lshl_b32 s100, s64, 20
	s_lshl_b32 s101, s65, 10
	s_add_u32 s98, s20, s100
	s_addc_u32 s99, s21, 0
	s_add_u32 s98, s98, s101
	s_addc_u32 s99, s99, 0
	s_waitcnt vmcnt(0) lgkmcnt(0)
	v_mov_b32_e32 v143, v142
	v_mov_b32_e32 v178, v218
	v_pk_mul_f32 v[126:127], v[126:127], v[178:179] op_sel_hi:[1,0]
	v_pk_mul_f32 v[128:129], v[128:129], v[178:179] op_sel_hi:[1,0]
	v_pk_mul_f32 v[126:127], v[202:203], v[126:127]
	v_pk_mul_f32 v[128:129], v[204:205], v[128:129]
	global_store_dwordx4 v143, v[126:129], s[98:99]
	v_pk_mul_f32 v[122:123], v[122:123], v[178:179] op_sel_hi:[1,0]
	v_pk_mul_f32 v[124:125], v[124:125], v[178:179] op_sel_hi:[1,0]
	v_pk_mul_f32 v[122:123], v[206:207], v[122:123]
	v_pk_mul_f32 v[124:125], v[208:209], v[124:125]
	global_store_dwordx4 v143, v[122:125], s[98:99] offset:64
	v_pk_mul_f32 v[110:111], v[110:111], v[178:179] op_sel_hi:[1,0]
	v_pk_mul_f32 v[112:113], v[112:113], v[178:179] op_sel_hi:[1,0]
	v_pk_mul_f32 v[110:111], v[210:211], v[110:111]
	v_pk_mul_f32 v[112:113], v[212:213], v[112:113]
	global_store_dwordx4 v143, v[110:113], s[98:99] offset:512
	v_pk_mul_f32 v[106:107], v[106:107], v[178:179] op_sel_hi:[1,0]
	v_pk_mul_f32 v[108:109], v[108:109], v[178:179] op_sel_hi:[1,0]
	v_pk_mul_f32 v[106:107], v[214:215], v[106:107]
	v_pk_mul_f32 v[108:109], v[216:217], v[108:109]
	global_store_dwordx4 v143, v[106:109], s[98:99] offset:576
	v_add_u32_e32 v143, 0x10000, v142
	v_mov_b32_e32 v178, v219
	v_pk_mul_f32 v[118:119], v[118:119], v[178:179] op_sel_hi:[1,0]
	v_pk_mul_f32 v[120:121], v[120:121], v[178:179] op_sel_hi:[1,0]
	v_pk_mul_f32 v[118:119], v[202:203], v[118:119]
	v_pk_mul_f32 v[120:121], v[204:205], v[120:121]
	global_store_dwordx4 v143, v[118:121], s[98:99]
	v_pk_mul_f32 v[114:115], v[114:115], v[178:179] op_sel_hi:[1,0]
	v_pk_mul_f32 v[116:117], v[116:117], v[178:179] op_sel_hi:[1,0]
	v_pk_mul_f32 v[114:115], v[206:207], v[114:115]
	v_pk_mul_f32 v[116:117], v[208:209], v[116:117]
	global_store_dwordx4 v143, v[114:117], s[98:99] offset:64
	v_pk_mul_f32 v[102:103], v[102:103], v[178:179] op_sel_hi:[1,0]
	v_pk_mul_f32 v[104:105], v[104:105], v[178:179] op_sel_hi:[1,0]
	v_pk_mul_f32 v[102:103], v[210:211], v[102:103]
	v_pk_mul_f32 v[104:105], v[212:213], v[104:105]
	global_store_dwordx4 v143, v[102:105], s[98:99] offset:512
	v_pk_mul_f32 v[98:99], v[98:99], v[178:179] op_sel_hi:[1,0]
	v_pk_mul_f32 v[100:101], v[100:101], v[178:179] op_sel_hi:[1,0]
	v_pk_mul_f32 v[98:99], v[214:215], v[98:99]
	v_pk_mul_f32 v[100:101], v[216:217], v[100:101]
	global_store_dwordx4 v143, v[98:101], s[98:99] offset:576
	v_add_u32_e32 v143, 0x20000, v142
	v_mov_b32_e32 v178, v220
	v_pk_mul_f32 v[94:95], v[94:95], v[178:179] op_sel_hi:[1,0]
	v_pk_mul_f32 v[96:97], v[96:97], v[178:179] op_sel_hi:[1,0]
	v_pk_mul_f32 v[94:95], v[202:203], v[94:95]
	v_pk_mul_f32 v[96:97], v[204:205], v[96:97]
	global_store_dwordx4 v143, v[94:97], s[98:99]
	v_pk_mul_f32 v[90:91], v[90:91], v[178:179] op_sel_hi:[1,0]
	v_pk_mul_f32 v[92:93], v[92:93], v[178:179] op_sel_hi:[1,0]
	v_pk_mul_f32 v[90:91], v[206:207], v[90:91]
	v_pk_mul_f32 v[92:93], v[208:209], v[92:93]
	global_store_dwordx4 v143, v[90:93], s[98:99] offset:64
	v_pk_mul_f32 v[78:79], v[78:79], v[178:179] op_sel_hi:[1,0]
	v_pk_mul_f32 v[80:81], v[80:81], v[178:179] op_sel_hi:[1,0]
	v_pk_mul_f32 v[78:79], v[210:211], v[78:79]
	v_pk_mul_f32 v[80:81], v[212:213], v[80:81]
	global_store_dwordx4 v143, v[78:81], s[98:99] offset:512
	v_pk_mul_f32 v[74:75], v[74:75], v[178:179] op_sel_hi:[1,0]
	v_pk_mul_f32 v[76:77], v[76:77], v[178:179] op_sel_hi:[1,0]
	v_pk_mul_f32 v[74:75], v[214:215], v[74:75]
	v_pk_mul_f32 v[76:77], v[216:217], v[76:77]
; #define GAS __attribute__((address_space(1)))
; __device__ __forceinline__ void rms_row2_f32(float* xrow0, const float* g, int lane, bool second_valid) {
;     const int hl = lane & 31, hw = lane >> 5;
;     if (hw && !second_valid) return;
;     GAS f32x4* xr = (GAS f32x4*)(xrow0 + (size_t)hw * DM) + hl; const GAS f32x4* gr = (const GAS f32x4*)g + hl;
;     f32x4 v[8]; float s = 0.f;
; #pragma unroll
;     for (int j = 0; j < 8; ++j) { v[j] = NTL(xr + 32 * j); s += (v[j].x * v[j].x + v[j].y * v[j].y) + (v[j].z * v[j].z + v[j].w * v[j].w); }
; #pragma unroll
;     for (int o = 1; o < 32; o <<= 1) s += __shfl_xor(s, o);
;     const float rstd = 1.f / sqrtf(s * (1.f / DM) + EPS);
; #pragma unroll
;     for (int j = 0; j < 8; ++j) { const f32x4 gg = gr[32 * j]; xr[32 * j] = v[j] * rstd * gg; }
	global_store_dwordx4 v143, v[74:77], s[98:99] offset:576
	v_add_u32_e32 v143, 0x30000, v142
	v_mov_b32_e32 v178, v221
	v_pk_mul_f32 v[86:87], v[86:87], v[178:179] op_sel_hi:[1,0]
	v_pk_mul_f32 v[88:89], v[88:89], v[178:179] op_sel_hi:[1,0]
	v_pk_mul_f32 v[86:87], v[202:203], v[86:87]
	v_pk_mul_f32 v[88:89], v[204:205], v[88:89]
	global_store_dwordx4 v143, v[86:89], s[98:99]
	v_pk_mul_f32 v[82:83], v[82:83], v[178:179] op_sel_hi:[1,0]
	v_pk_mul_f32 v[84:85], v[84:85], v[178:179] op_sel_hi:[1,0]
	v_pk_mul_f32 v[82:83], v[206:207], v[82:83]
	v_pk_mul_f32 v[84:85], v[208:209], v[84:85]
	global_store_dwordx4 v143, v[82:85], s[98:99] offset:64
	v_pk_mul_f32 v[70:71], v[70:71], v[178:179] op_sel_hi:[1,0]
	v_pk_mul_f32 v[72:73], v[72:73], v[178:179] op_sel_hi:[1,0]
	v_pk_mul_f32 v[70:71], v[210:211], v[70:71]
	v_pk_mul_f32 v[72:73], v[212:213], v[72:73]
	global_store_dwordx4 v143, v[70:73], s[98:99] offset:512
	v_pk_mul_f32 v[66:67], v[66:67], v[178:179] op_sel_hi:[1,0]
	v_pk_mul_f32 v[68:69], v[68:69], v[178:179] op_sel_hi:[1,0]
	v_pk_mul_f32 v[66:67], v[214:215], v[66:67]
	v_pk_mul_f32 v[68:69], v[216:217], v[68:69]
	global_store_dwordx4 v143, v[66:69], s[98:99] offset:576
	v_add_u32_e32 v143, 0x80000, v142
	v_mov_b32_e32 v178, v222
	v_pk_mul_f32 v[62:63], v[62:63], v[178:179] op_sel_hi:[1,0]
	v_pk_mul_f32 v[64:65], v[64:65], v[178:179] op_sel_hi:[1,0]
	v_pk_mul_f32 v[62:63], v[202:203], v[62:63]
	v_pk_mul_f32 v[64:65], v[204:205], v[64:65]
	global_store_dwordx4 v143, v[62:65], s[98:99]
	v_pk_mul_f32 v[58:59], v[58:59], v[178:179] op_sel_hi:[1,0]
	v_pk_mul_f32 v[60:61], v[60:61], v[178:179] op_sel_hi:[1,0]
	v_pk_mul_f32 v[58:59], v[206:207], v[58:59]
	v_pk_mul_f32 v[60:61], v[208:209], v[60:61]
	global_store_dwordx4 v143, v[58:61], s[98:99] offset:64
	v_pk_mul_f32 v[46:47], v[46:47], v[178:179] op_sel_hi:[1,0]
	v_pk_mul_f32 v[48:49], v[48:49], v[178:179] op_sel_hi:[1,0]
	v_pk_mul_f32 v[46:47], v[210:211], v[46:47]
	v_pk_mul_f32 v[48:49], v[212:213], v[48:49]
	global_store_dwordx4 v143, v[46:49], s[98:99] offset:512
	v_pk_mul_f32 v[42:43], v[42:43], v[178:179] op_sel_hi:[1,0]
	v_pk_mul_f32 v[44:45], v[44:45], v[178:179] op_sel_hi:[1,0]
	v_pk_mul_f32 v[42:43], v[214:215], v[42:43]
	v_pk_mul_f32 v[44:45], v[216:217], v[44:45]
	global_store_dwordx4 v143, v[42:45], s[98:99] offset:576
	v_add_u32_e32 v143, 0x90000, v142
	v_mov_b32_e32 v178, v223
	v_pk_mul_f32 v[54:55], v[54:55], v[178:179] op_sel_hi:[1,0]
	v_pk_mul_f32 v[56:57], v[56:57], v[178:179] op_sel_hi:[1,0]
	v_pk_mul_f32 v[54:55], v[202:203], v[54:55]
	v_pk_mul_f32 v[56:57], v[204:205], v[56:57]
	global_store_dwordx4 v143, v[54:57], s[98:99]
	v_pk_mul_f32 v[50:51], v[50:51], v[178:179] op_sel_hi:[1,0]
	v_pk_mul_f32 v[52:53], v[52:53], v[178:179] op_sel_hi:[1,0]
	v_pk_mul_f32 v[50:51], v[206:207], v[50:51]
	v_pk_mul_f32 v[52:53], v[208:209], v[52:53]
	global_store_dwordx4 v143, v[50:53], s[98:99] offset:64
	v_pk_mul_f32 v[38:39], v[38:39], v[178:179] op_sel_hi:[1,0]
	v_pk_mul_f32 v[40:41], v[40:41], v[178:179] op_sel_hi:[1,0]
	v_pk_mul_f32 v[38:39], v[210:211], v[38:39]
	v_pk_mul_f32 v[40:41], v[212:213], v[40:41]
	global_store_dwordx4 v143, v[38:41], s[98:99] offset:512
	v_pk_mul_f32 v[34:35], v[34:35], v[178:179] op_sel_hi:[1,0]
	v_pk_mul_f32 v[36:37], v[36:37], v[178:179] op_sel_hi:[1,0]
	v_pk_mul_f32 v[34:35], v[214:215], v[34:35]
	v_pk_mul_f32 v[36:37], v[216:217], v[36:37]
	global_store_dwordx4 v143, v[34:37], s[98:99] offset:576
	v_add_u32_e32 v143, 0xa0000, v142
	v_mov_b32_e32 v178, v224
	v_pk_mul_f32 v[30:31], v[30:31], v[178:179] op_sel_hi:[1,0]
	v_pk_mul_f32 v[32:33], v[32:33], v[178:179] op_sel_hi:[1,0]
	v_pk_mul_f32 v[30:31], v[202:203], v[30:31]
	v_pk_mul_f32 v[32:33], v[204:205], v[32:33]
	global_store_dwordx4 v143, v[30:33], s[98:99]
	v_pk_mul_f32 v[26:27], v[26:27], v[178:179] op_sel_hi:[1,0]
	v_pk_mul_f32 v[28:29], v[28:29], v[178:179] op_sel_hi:[1,0]
	v_pk_mul_f32 v[26:27], v[206:207], v[26:27]
	v_pk_mul_f32 v[28:29], v[208:209], v[28:29]
	global_store_dwordx4 v143, v[26:29], s[98:99] offset:64
	v_pk_mul_f32 v[18:19], v[18:19], v[178:179] op_sel_hi:[1,0]
	v_pk_mul_f32 v[20:21], v[20:21], v[178:179] op_sel_hi:[1,0]
	v_pk_mul_f32 v[18:19], v[210:211], v[18:19]
	v_pk_mul_f32 v[20:21], v[212:213], v[20:21]
	global_store_dwordx4 v143, v[18:21], s[98:99] offset:512
	v_pk_mul_f32 v[10:11], v[10:11], v[178:179] op_sel_hi:[1,0]
	v_pk_mul_f32 v[12:13], v[12:13], v[178:179] op_sel_hi:[1,0]
	v_pk_mul_f32 v[10:11], v[214:215], v[10:11]
	v_pk_mul_f32 v[12:13], v[216:217], v[12:13]
	global_store_dwordx4 v143, v[10:13], s[98:99] offset:576
	v_add_u32_e32 v143, 0xb0000, v142
	v_mov_b32_e32 v178, v225
	v_pk_mul_f32 v[22:23], v[22:23], v[178:179] op_sel_hi:[1,0]
	v_pk_mul_f32 v[24:25], v[24:25], v[178:179] op_sel_hi:[1,0]
	v_pk_mul_f32 v[22:23], v[202:203], v[22:23]
	v_pk_mul_f32 v[24:25], v[204:205], v[24:25]
	global_store_dwordx4 v143, v[22:25], s[98:99]
	v_pk_mul_f32 v[14:15], v[14:15], v[178:179] op_sel_hi:[1,0]
	v_pk_mul_f32 v[16:17], v[16:17], v[178:179] op_sel_hi:[1,0]
	v_pk_mul_f32 v[14:15], v[206:207], v[14:15]
	v_pk_mul_f32 v[16:17], v[208:209], v[16:17]
	global_store_dwordx4 v143, v[14:17], s[98:99] offset:64
	v_pk_mul_f32 v[6:7], v[6:7], v[178:179] op_sel_hi:[1,0]
	v_pk_mul_f32 v[8:9], v[8:9], v[178:179] op_sel_hi:[1,0]
	v_pk_mul_f32 v[6:7], v[210:211], v[6:7]
	v_pk_mul_f32 v[8:9], v[212:213], v[8:9]
	global_store_dwordx4 v143, v[6:9], s[98:99] offset:512
	v_pk_mul_f32 v[2:3], v[2:3], v[178:179] op_sel_hi:[1,0]
	v_pk_mul_f32 v[4:5], v[4:5], v[178:179] op_sel_hi:[1,0]
	v_pk_mul_f32 v[2:3], v[214:215], v[2:3]
	v_pk_mul_f32 v[4:5], v[216:217], v[4:5]
	global_store_dwordx4 v143, v[2:5], s[98:99] offset:576
	s_mov_b64 s[42:43], -1
	s_and_b64 vcc, exec, s[6:7]
	s_cbranch_vccnz .LBB0_1886
	s_andn2_b64 vcc, exec, s[14:15]
	s_cbranch_vccnz .LBB0_1885
	s_barrier
	s_branch .LBB0_1885

;     __device__ __forceinline__ Pre pre4(int row, int col) const { const size_t o = (size_t)row * DM + col; Pre p; p.g = NTL((const v2u*)(SG + o)); p.m = (v2u){0u, 0u}; if (MODE == 1) p.m = NTL((const v2u*)(MG + o)); return p; }
;     __device__ __forceinline__ Pre pre4(int row, int col) const { const float* sb = (row < TP) ? srcP : srcS - (size_t)TP * DM; Pre p; p.s = NTL((const f32x4*)(sb + (size_t)row * DM + col)); return p; }
;     __device__ __forceinline__ float store4pg(int row, int col, f32x4 a, const Pre& p, f32x4 gg) const {
;         const size_t o = (size_t)row * DM + col; const f32x4 v = p.s + a * alpha; *(f32x4*)(out + o) = v;
;     __device__ __forceinline__ void operator()(const f32x4 (&acc)[2][2][4][2], const Unit& u, int wr, int wc, int fr, int fq) const {
;     ...
;         for (int am = 0; am < 4; ++am) {
;             const int ai = am >> 1, mb = (am & 1) * 2;
;             Pre pv[2][2][2];
; #pragma unroll
;             for (int mm = 0; mm < 2; ++mm)
; #pragma unroll
;                 for (int bj = 0; bj < 2; ++bj)
; #pragma unroll
;                     for (int n = 0; n < 2; ++n) pv[mm][bj][n] = pre4(row0 + ai * HALF + (mb + mm) * 16, col0 + bj * HALF + n * 16);
; #pragma unroll
;             for (int mm = 0; mm < 2; ++mm) { const int m = mb + mm; float ss = 0.f;
; #pragma unroll
;                 for (int bj = 0; bj < 2; ++bj)
; #pragma unroll
;                     for (int n = 0; n < 2; ++n) ss += store4pg(row0 + ai * HALF + m * 16, col0 + bj * HALF + n * 16, acc[ai][bj][m][n], pv[mm][bj][n], gg[bj][n]);
.LBB0_1931:
	s_lshl_b32 s100, s64, 20
	s_lshl_b32 s101, s65, 10
	s_add_u32 s98, s20, s100
	s_addc_u32 s99, s21, 0
	s_add_u32 s98, s98, s101
	s_addc_u32 s99, s99, 0
	v_lshlrev_b32_e32 v142, 12, v144
	v_lshl_add_u32 v142, v146, 2, v142
	v_mov_b32_e32 v143, v142
	global_load_dwordx4 v[150:153], v143, s[98:99]
	global_load_dwordx4 v[154:157], v143, s[98:99] offset:64
	global_load_dwordx4 v[158:161], v143, s[98:99] offset:512
	global_load_dwordx4 v[162:165], v143, s[98:99] offset:576
	v_add_u32_e32 v143, 0x10000, v142
	global_load_dwordx4 v[166:169], v143, s[98:99]
	global_load_dwordx4 v[170:173], v143, s[98:99] offset:64
	global_load_dwordx4 v[174:177], v143, s[98:99] offset:512
	global_load_dwordx4 v[178:181], v143, s[98:99] offset:576
	v_add_u32_e32 v143, 0x20000, v142
	global_load_dwordx4 v[182:185], v143, s[98:99]
	global_load_dwordx4 v[186:189], v143, s[98:99] offset:64
	global_load_dwordx4 v[190:193], v143, s[98:99] offset:512
	global_load_dwordx4 v[194:197], v143, s[98:99] offset:576
	v_add_u32_e32 v143, 0x30000, v142
	global_load_dwordx4 v[198:201], v143, s[98:99]
	global_load_dwordx4 v[202:205], v143, s[98:99] offset:64
	global_load_dwordx4 v[206:209], v143, s[98:99] offset:512
	global_load_dwordx4 v[210:213], v143, s[98:99] offset:576
	s_waitcnt vmcnt(8)
	v_pk_fma_f32 v[126:127], v[126:127], 0.5, v[150:151] op_sel_hi:[1,0,1]
	v_pk_fma_f32 v[128:129], v[128:129], 0.5, v[152:153] op_sel_hi:[1,0,1]
	v_pk_fma_f32 v[122:123], v[122:123], 0.5, v[154:155] op_sel_hi:[1,0,1]
	v_pk_fma_f32 v[124:125], v[124:125], 0.5, v[156:157] op_sel_hi:[1,0,1]
	v_pk_fma_f32 v[110:111], v[110:111], 0.5, v[158:159] op_sel_hi:[1,0,1]
	v_pk_fma_f32 v[112:113], v[112:113], 0.5, v[160:161] op_sel_hi:[1,0,1]
	v_pk_fma_f32 v[106:107], v[106:107], 0.5, v[162:163] op_sel_hi:[1,0,1]
	v_pk_fma_f32 v[108:109], v[108:109], 0.5, v[164:165] op_sel_hi:[1,0,1]
	v_pk_fma_f32 v[118:119], v[118:119], 0.5, v[166:167] op_sel_hi:[1,0,1]
	v_pk_fma_f32 v[120:121], v[120:121], 0.5, v[168:169] op_sel_hi:[1,0,1]
	v_pk_fma_f32 v[114:115], v[114:115], 0.5, v[170:171] op_sel_hi:[1,0,1]
	v_pk_fma_f32 v[116:117], v[116:117], 0.5, v[172:173] op_sel_hi:[1,0,1]
	v_pk_fma_f32 v[102:103], v[102:103], 0.5, v[174:175] op_sel_hi:[1,0,1]
	v_pk_fma_f32 v[104:105], v[104:105], 0.5, v[176:177] op_sel_hi:[1,0,1]
	v_pk_fma_f32 v[98:99], v[98:99], 0.5, v[178:179] op_sel_hi:[1,0,1]
	v_pk_fma_f32 v[100:101], v[100:101], 0.5, v[180:181] op_sel_hi:[1,0,1]
	v_add_u32_e32 v143, 0x80000, v142
	global_load_dwordx4 v[150:153], v143, s[98:99]
	global_load_dwordx4 v[154:157], v143, s[98:99] offset:64
	global_load_dwordx4 v[158:161], v143, s[98:99] offset:512
	global_load_dwordx4 v[162:165], v143, s[98:99] offset:576
	v_add_u32_e32 v143, 0x90000, v142
	global_load_dwordx4 v[166:169], v143, s[98:99]
	global_load_dwordx4 v[170:173], v143, s[98:99] offset:64
	global_load_dwordx4 v[174:177], v143, s[98:99] offset:512
	global_load_dwordx4 v[178:181], v143, s[98:99] offset:576
	s_waitcnt vmcnt(8)
	v_pk_fma_f32 v[94:95], v[94:95], 0.5, v[182:183] op_sel_hi:[1,0,1]
	v_pk_fma_f32 v[96:97], v[96:97], 0.5, v[184:185] op_sel_hi:[1,0,1]
	v_pk_fma_f32 v[90:91], v[90:91], 0.5, v[186:187] op_sel_hi:[1,0,1]
	v_pk_fma_f32 v[92:93], v[92:93], 0.5, v[188:189] op_sel_hi:[1,0,1]
	v_pk_fma_f32 v[78:79], v[78:79], 0.5, v[190:191] op_sel_hi:[1,0,1]
	v_pk_fma_f32 v[80:81], v[80:81], 0.5, v[192:193] op_sel_hi:[1,0,1]
	v_pk_fma_f32 v[74:75], v[74:75], 0.5, v[194:195] op_sel_hi:[1,0,1]
	v_pk_fma_f32 v[76:77], v[76:77], 0.5, v[196:197] op_sel_hi:[1,0,1]
	v_pk_fma_f32 v[86:87], v[86:87], 0.5, v[198:199] op_sel_hi:[1,0,1]
	v_pk_fma_f32 v[88:89], v[88:89], 0.5, v[200:201] op_sel_hi:[1,0,1]
	v_pk_fma_f32 v[82:83], v[82:83], 0.5, v[202:203] op_sel_hi:[1,0,1]
	v_pk_fma_f32 v[84:85], v[84:85], 0.5, v[204:205] op_sel_hi:[1,0,1]
	v_pk_fma_f32 v[70:71], v[70:71], 0.5, v[206:207] op_sel_hi:[1,0,1]
	v_pk_fma_f32 v[72:73], v[72:73], 0.5, v[208:209] op_sel_hi:[1,0,1]
	v_pk_fma_f32 v[66:67], v[66:67], 0.5, v[210:211] op_sel_hi:[1,0,1]
	v_pk_fma_f32 v[68:69], v[68:69], 0.5, v[212:213] op_sel_hi:[1,0,1]
	v_add_u32_e32 v143, 0xa0000, v142
	global_load_dwordx4 v[182:185], v143, s[98:99]
	global_load_dwordx4 v[186:189], v143, s[98:99] offset:64
	global_load_dwordx4 v[190:193], v143, s[98:99] offset:512
	global_load_dwordx4 v[194:197], v143, s[98:99] offset:576
	v_add_u32_e32 v143, 0xb0000, v142
	global_load_dwordx4 v[198:201], v143, s[98:99]
	global_load_dwordx4 v[202:205], v143, s[98:99] offset:64
	global_load_dwordx4 v[206:209], v143, s[98:99] offset:512
	global_load_dwordx4 v[210:213], v143, s[98:99] offset:576
	s_waitcnt vmcnt(8)
	v_pk_fma_f32 v[62:63], v[62:63], 0.5, v[150:151] op_sel_hi:[1,0,1]
	v_pk_fma_f32 v[64:65], v[64:65], 0.5, v[152:153] op_sel_hi:[1,0,1]
	v_pk_fma_f32 v[58:59], v[58:59], 0.5, v[154:155] op_sel_hi:[1,0,1]
	v_pk_fma_f32 v[60:61], v[60:61], 0.5, v[156:157] op_sel_hi:[1,0,1]
	v_pk_fma_f32 v[46:47], v[46:47], 0.5, v[158:159] op_sel_hi:[1,0,1]
	v_pk_fma_f32 v[48:49], v[48:49], 0.5, v[160:161] op_sel_hi:[1,0,1]
	v_pk_fma_f32 v[42:43], v[42:43], 0.5, v[162:163] op_sel_hi:[1,0,1]
	v_pk_fma_f32 v[44:45], v[44:45], 0.5, v[164:165] op_sel_hi:[1,0,1]
	v_pk_fma_f32 v[54:55], v[54:55], 0.5, v[166:167] op_sel_hi:[1,0,1]
	v_pk_fma_f32 v[56:57], v[56:57], 0.5, v[168:169] op_sel_hi:[1,0,1]
	v_pk_fma_f32 v[50:51], v[50:51], 0.5, v[170:171] op_sel_hi:[1,0,1]
	v_pk_fma_f32 v[52:53], v[52:53], 0.5, v[172:173] op_sel_hi:[1,0,1]
	v_pk_fma_f32 v[38:39], v[38:39], 0.5, v[174:175] op_sel_hi:[1,0,1]
	v_pk_fma_f32 v[40:41], v[40:41], 0.5, v[176:177] op_sel_hi:[1,0,1]
	v_pk_fma_f32 v[34:35], v[34:35], 0.5, v[178:179] op_sel_hi:[1,0,1]
	v_pk_fma_f32 v[36:37], v[36:37], 0.5, v[180:181] op_sel_hi:[1,0,1]
	s_waitcnt vmcnt(0)
; __device__ __forceinline__ unsigned pk2(float lo, float hi) { const f32x2_t_ v = {lo, hi}; return __builtin_bit_cast(unsigned, __builtin_convertvector(v, bf16x2_t_)); }
;     __device__ __forceinline__ float store4pg(int row, int col, f32x4 a, const Pre& p, f32x4 gg) const {
;         const size_t o = (size_t)row * DM + col; const f32x4 v = p.s + a * alpha; *(f32x4*)(out + o) = v;
;         if (XNo) { v2u w; w.x = pk2(v[0] * gg[0], v[1] * gg[1]); w.y = pk2(v[2] * gg[2], v[3] * gg[3]); *(v2u*)(XNo + o) = w; return (v[0] * v[0] + v[1] * v[1]) + (v[2] * v[2] + v[3] * v[3]); }
;     __device__ __forceinline__ void operator()(const f32x4 (&acc)[2][2][4][2], const Unit& u, int wr, int wc, int fr, int fq) const {
;     ...
;             for (int mm = 0; mm < 2; ++mm) { const int m = mb + mm; float ss = 0.f;
; #pragma unroll
;                 for (int bj = 0; bj < 2; ++bj)
; #pragma unroll
;                     for (int n = 0; n < 2; ++n) ss += store4pg(row0 + ai * HALF + m * 16, col0 + bj * HALF + n * 16, acc[ai][bj][m][n], pv[mm][bj][n], gg[bj][n]);
;                 if (norm) { ss += __shfl_xor(ss, 16); ss += __shfl_xor(ss, 32); if (fq == 0) (void)__hip_atomic_fetch_add(ROWSUM + ai * HALF + wr * 64 + m * 16 + fr, ss, __ATOMIC_RELAXED, __HIP_MEMORY_SCOPE_WORKGROUP); } }
;         }
;         if (norm) { asm volatile("s_waitcnt lgkmcnt(0)" ::: "memory"); __builtin_amdgcn_s_barrier(); asm volatile("" ::: "memory");
;             if (threadIdx.x < 256) PP[(size_t)(u.pm * BM + threadIdx.x) * 4 + u.pn] = ROWSUM[threadIdx.x]; }
	v_pk_fma_f32 v[30:31], v[30:31], 0.5, v[182:183] op_sel_hi:[1,0,1]
	v_pk_fma_f32 v[32:33], v[32:33], 0.5, v[184:185] op_sel_hi:[1,0,1]
	v_pk_fma_f32 v[26:27], v[26:27], 0.5, v[186:187] op_sel_hi:[1,0,1]
	v_pk_fma_f32 v[28:29], v[28:29], 0.5, v[188:189] op_sel_hi:[1,0,1]
	v_pk_fma_f32 v[18:19], v[18:19], 0.5, v[190:191] op_sel_hi:[1,0,1]
	v_pk_fma_f32 v[20:21], v[20:21], 0.5, v[192:193] op_sel_hi:[1,0,1]
	v_pk_fma_f32 v[10:11], v[10:11], 0.5, v[194:195] op_sel_hi:[1,0,1]
	v_pk_fma_f32 v[12:13], v[12:13], 0.5, v[196:197] op_sel_hi:[1,0,1]
	v_pk_fma_f32 v[22:23], v[22:23], 0.5, v[198:199] op_sel_hi:[1,0,1]
	v_pk_fma_f32 v[24:25], v[24:25], 0.5, v[200:201] op_sel_hi:[1,0,1]
	v_pk_fma_f32 v[14:15], v[14:15], 0.5, v[202:203] op_sel_hi:[1,0,1]
	v_pk_fma_f32 v[16:17], v[16:17], 0.5, v[204:205] op_sel_hi:[1,0,1]
	v_pk_fma_f32 v[6:7], v[6:7], 0.5, v[206:207] op_sel_hi:[1,0,1]
	v_pk_fma_f32 v[8:9], v[8:9], 0.5, v[208:209] op_sel_hi:[1,0,1]
	v_pk_fma_f32 v[2:3], v[2:3], 0.5, v[210:211] op_sel_hi:[1,0,1]
	v_pk_fma_f32 v[4:5], v[4:5], 0.5, v[212:213] op_sel_hi:[1,0,1]
	s_load_dwordx2 s[100:101], s[0:1], 0xa0
	v_lshlrev_b32_e32 v178, 2, v146
	s_lshl_b32 s98, s65, 10
	v_add_u32_e32 v178, s98, v178
	s_waitcnt lgkmcnt(0)
	global_load_dwordx4 v[182:185], v178, s[100:101]
	global_load_dwordx4 v[186:189], v178, s[100:101] offset:64
	global_load_dwordx4 v[190:193], v178, s[100:101] offset:512
	global_load_dwordx4 v[194:197], v178, s[100:101] offset:576
	v_pk_mul_f32 v[158:159], v[126:127], v[126:127]
	v_pk_fma_f32 v[158:159], v[128:129], v[128:129], v[158:159]
	v_pk_fma_f32 v[158:159], v[122:123], v[122:123], v[158:159]
	v_pk_fma_f32 v[158:159], v[124:125], v[124:125], v[158:159]
	v_pk_fma_f32 v[158:159], v[110:111], v[110:111], v[158:159]
	v_pk_fma_f32 v[158:159], v[112:113], v[112:113], v[158:159]
	v_pk_fma_f32 v[158:159], v[106:107], v[106:107], v[158:159]
	v_pk_fma_f32 v[158:159], v[108:109], v[108:109], v[158:159]
	v_add_f32_e32 v150, v158, v159
	v_pk_mul_f32 v[158:159], v[118:119], v[118:119]
	v_pk_fma_f32 v[158:159], v[120:121], v[120:121], v[158:159]
	v_pk_fma_f32 v[158:159], v[114:115], v[114:115], v[158:159]
	v_pk_fma_f32 v[158:159], v[116:117], v[116:117], v[158:159]
	v_pk_fma_f32 v[158:159], v[102:103], v[102:103], v[158:159]
	v_pk_fma_f32 v[158:159], v[104:105], v[104:105], v[158:159]
	v_pk_fma_f32 v[158:159], v[98:99], v[98:99], v[158:159]
	v_pk_fma_f32 v[158:159], v[100:101], v[100:101], v[158:159]
	v_add_f32_e32 v151, v158, v159
	v_pk_mul_f32 v[158:159], v[94:95], v[94:95]
	v_pk_fma_f32 v[158:159], v[96:97], v[96:97], v[158:159]
	v_pk_fma_f32 v[158:159], v[90:91], v[90:91], v[158:159]
	v_pk_fma_f32 v[158:159], v[92:93], v[92:93], v[158:159]
	v_pk_fma_f32 v[158:159], v[78:79], v[78:79], v[158:159]
	v_pk_fma_f32 v[158:159], v[80:81], v[80:81], v[158:159]
	v_pk_fma_f32 v[158:159], v[74:75], v[74:75], v[158:159]
	v_pk_fma_f32 v[158:159], v[76:77], v[76:77], v[158:159]
	v_add_f32_e32 v152, v158, v159
	v_pk_mul_f32 v[158:159], v[86:87], v[86:87]
	v_pk_fma_f32 v[158:159], v[88:89], v[88:89], v[158:159]
	v_pk_fma_f32 v[158:159], v[82:83], v[82:83], v[158:159]
	v_pk_fma_f32 v[158:159], v[84:85], v[84:85], v[158:159]
	v_pk_fma_f32 v[158:159], v[70:71], v[70:71], v[158:159]
	v_pk_fma_f32 v[158:159], v[72:73], v[72:73], v[158:159]
	v_pk_fma_f32 v[158:159], v[66:67], v[66:67], v[158:159]
	v_pk_fma_f32 v[158:159], v[68:69], v[68:69], v[158:159]
	v_add_f32_e32 v153, v158, v159
	v_pk_mul_f32 v[158:159], v[62:63], v[62:63]
	v_pk_fma_f32 v[158:159], v[64:65], v[64:65], v[158:159]
	v_pk_fma_f32 v[158:159], v[58:59], v[58:59], v[158:159]
	v_pk_fma_f32 v[158:159], v[60:61], v[60:61], v[158:159]
	v_pk_fma_f32 v[158:159], v[46:47], v[46:47], v[158:159]
	v_pk_fma_f32 v[158:159], v[48:49], v[48:49], v[158:159]
	v_pk_fma_f32 v[158:159], v[42:43], v[42:43], v[158:159]
	v_pk_fma_f32 v[158:159], v[44:45], v[44:45], v[158:159]
	v_add_f32_e32 v154, v158, v159
	v_pk_mul_f32 v[158:159], v[54:55], v[54:55]
	v_pk_fma_f32 v[158:159], v[56:57], v[56:57], v[158:159]
	v_pk_fma_f32 v[158:159], v[50:51], v[50:51], v[158:159]
	v_pk_fma_f32 v[158:159], v[52:53], v[52:53], v[158:159]
	v_pk_fma_f32 v[158:159], v[38:39], v[38:39], v[158:159]
	v_pk_fma_f32 v[158:159], v[40:41], v[40:41], v[158:159]
	v_pk_fma_f32 v[158:159], v[34:35], v[34:35], v[158:159]
	v_pk_fma_f32 v[158:159], v[36:37], v[36:37], v[158:159]
	v_add_f32_e32 v155, v158, v159
	v_pk_mul_f32 v[158:159], v[30:31], v[30:31]
	v_pk_fma_f32 v[158:159], v[32:33], v[32:33], v[158:159]
	v_pk_fma_f32 v[158:159], v[26:27], v[26:27], v[158:159]
	v_pk_fma_f32 v[158:159], v[28:29], v[28:29], v[158:159]
	v_pk_fma_f32 v[158:159], v[18:19], v[18:19], v[158:159]
	v_pk_fma_f32 v[158:159], v[20:21], v[20:21], v[158:159]
	v_pk_fma_f32 v[158:159], v[10:11], v[10:11], v[158:159]
	v_pk_fma_f32 v[158:159], v[12:13], v[12:13], v[158:159]
	v_add_f32_e32 v156, v158, v159
	v_pk_mul_f32 v[158:159], v[22:23], v[22:23]
	v_pk_fma_f32 v[158:159], v[24:25], v[24:25], v[158:159]
	v_pk_fma_f32 v[158:159], v[14:15], v[14:15], v[158:159]
	v_pk_fma_f32 v[158:159], v[16:17], v[16:17], v[158:159]
	v_pk_fma_f32 v[158:159], v[6:7], v[6:7], v[158:159]
	v_pk_fma_f32 v[158:159], v[8:9], v[8:9], v[158:159]
	v_pk_fma_f32 v[158:159], v[2:3], v[2:3], v[158:159]
	v_pk_fma_f32 v[158:159], v[4:5], v[4:5], v[158:159]
	v_add_f32_e32 v157, v158, v159
	v_and_b32_e32 v163, 0xff, v0
	v_lshlrev_b32_e32 v164, 2, v163
	v_add_u32_e32 v162, 0x20800, v164
	v_mov_b32_e32 v165, 0
	ds_write_b32 v162, v165
	s_waitcnt lgkmcnt(0)
	s_barrier
	v_lshlrev_b32_e32 v165, 2, v144
	v_add_u32_e32 v165, 0x20800, v165
	ds_add_f32 v165, v150
	ds_add_f32 v165, v151 offset:64
	ds_add_f32 v165, v152 offset:128
	ds_add_f32 v165, v153 offset:192
	ds_add_f32 v165, v154 offset:512
	ds_add_f32 v165, v155 offset:576
	ds_add_f32 v165, v156 offset:640
	ds_add_f32 v165, v157 offset:704
	s_waitcnt lgkmcnt(0)
	s_barrier
	ds_read_b32 v165, v162
	s_lshl_b32 s100, s64, 12
	s_add_u32 s98, s22, 0x20000
	s_addc_u32 s99, s23, 0
	s_add_u32 s98, s98, s100
	s_addc_u32 s99, s99, 0
	s_lshl_b32 s101, s65, 2
	v_lshlrev_b32_e32 v164, 4, v163
	v_add_u32_e32 v179, s101, v164
	s_waitcnt lgkmcnt(0)
	global_store_dword v179, v165, s[98:99] sc0 sc1
	s_mov_b32 s100, 0
; __device__ __forceinline__ float row_rstd(const float* PP, const float* PS, int row) {
;     float ss;
;     if (row < TP) { const f32x4 a = NTL((const f32x4*)(PP + (size_t)row * 4)); ss = (a[0] + a[1]) + (a[2] + a[3]); }
;     else { const f32x4* p = (const f32x4*)(PS + (size_t)(row - TP) * 16); const f32x4 a = (NTL(p) + NTL(p + 1)) + (NTL(p + 2) + NTL(p + 3)); ss = (a[0] + a[1]) + (a[2] + a[3]); }
;     return 1.0f / sqrtf(ss * (1.0f / DM) + EPS);
;     __device__ __forceinline__ void operator()(const f32x4 (&acc)[2][2][4][2], const Unit& u, int wr, int wc, int fr, int fq) const {
;     ...
;                 if (norm) { ss += __shfl_xor(ss, 16); ss += __shfl_xor(ss, 32); if (fq == 0) (void)__hip_atomic_fetch_add(ROWSUM + ai * HALF + wr * 64 + m * 16 + fr, ss, __ATOMIC_RELAXED, __HIP_MEMORY_SCOPE_WORKGROUP); } }
;         }
;         if (norm) { asm volatile("s_waitcnt lgkmcnt(0)" ::: "memory"); __builtin_amdgcn_s_barrier(); asm volatile("" ::: "memory");
;             if (threadIdx.x < 256) PP[(size_t)(u.pm * BM + threadIdx.x) * 4 + u.pn] = ROWSUM[threadIdx.x]; }
.Lp8f_b_poll:
	global_load_dwordx4 v[166:169], v164, s[98:99] sc0 sc1
	s_waitcnt vmcnt(0)
	v_min_u32_e32 v180, v166, v167
	v_min3_u32 v180, v180, v168, v169
	v_cmp_eq_u32_e32 vcc, 0, v180
	s_cbranch_vccz .Lp8f_b_got
	s_sleep 1
	s_add_i32 s100, s100, 1
	s_cmp_lt_u32 s100, 0x4000
	s_cbranch_scc1 .Lp8f_b_poll
.Lp8f_b_got:
	v_mov_b32_e32 v170, 0x358637bd
	v_mov_b32_e32 v171, 0x260
	v_add_f32_e32 v166, v166, v167
	v_add_f32_e32 v168, v168, v169
	v_add_f32_e32 v172, v166, v168
	v_fmamk_f32 v172, v172, 0x3a800000, v170
	v_mul_f32_e32 v174, 0x4f800000, v172
	s_mov_b32 s100, 0xf800000
	v_cmp_gt_f32_e32 vcc, s100, v172
	s_nop 1
	v_cndmask_b32_e32 v172, v172, v174, vcc
	v_sqrt_f32_e32 v174, v172
	s_nop 0
	v_add_u32_e32 v175, -1, v174
	v_add_u32_e32 v176, 1, v174
	v_fma_f32 v177, -v175, v174, v172
	v_fma_f32 v178, -v176, v174, v172
	v_cmp_ge_f32_e64 s[100:101], 0, v177
	s_nop 1
	v_cndmask_b32_e64 v174, v174, v175, s[100:101]
	v_cmp_lt_f32_e64 s[100:101], 0, v178
	s_nop 1
	v_cndmask_b32_e64 v174, v174, v176, s[100:101]
	v_mul_f32_e32 v175, 0x37800000, v174
	v_cndmask_b32_e32 v174, v174, v175, vcc
	v_cmp_class_f32_e32 vcc, v172, v171
	s_nop 1
	v_cndmask_b32_e32 v172, v174, v172, vcc
	v_div_scale_f32 v174, s[100:101], v172, v172, 1.0
	v_rcp_f32_e32 v175, v174
	v_div_scale_f32 v176, vcc, 1.0, v172, 1.0
	v_fma_f32 v177, -v174, v175, 1.0
	v_fmac_f32_e32 v175, v177, v175
	v_mul_f32_e32 v177, v176, v175
	v_fma_f32 v178, -v174, v177, v176
	v_fmac_f32_e32 v177, v178, v175
	v_fma_f32 v174, -v174, v177, v176
	v_div_fmas_f32 v174, v174, v175, v177
	v_div_fixup_f32 v174, v174, v172, 1.0
	v_add_u32_e32 v162, 0x800, v162
	ds_write_b32 v162, v174
	s_waitcnt lgkmcnt(0)
	s_barrier
	v_lshlrev_b32_e32 v165, 2, v144
	v_add_u32_e32 v165, 0x21000, v165
	ds_read_b32 v198, v165
	ds_read_b32 v199, v165 offset:64
	ds_read_b32 v200, v165 offset:128
	ds_read_b32 v201, v165 offset:192
	ds_read_b32 v202, v165 offset:512
	ds_read_b32 v203, v165 offset:576
	ds_read_b32 v204, v165 offset:640
	ds_read_b32 v205, v165 offset:704
	s_lshl_b32 s100, s64, 20
	s_lshl_b32 s101, s65, 10
	s_add_u32 s98, s20, s100
	s_addc_u32 s99, s21, 0
	s_add_u32 s98, s98, s101
	s_addc_u32 s99, s99, 0
	s_waitcnt vmcnt(0) lgkmcnt(0)
	v_mov_b32_e32 v143, v142
	v_mov_b32_e32 v158, v198
	v_pk_mul_f32 v[126:127], v[126:127], v[158:159] op_sel_hi:[1,0]
	v_pk_mul_f32 v[128:129], v[128:129], v[158:159] op_sel_hi:[1,0]
	v_pk_mul_f32 v[126:127], v[182:183], v[126:127]
	v_pk_mul_f32 v[128:129], v[184:185], v[128:129]
	global_store_dwordx4 v143, v[126:129], s[98:99]
	v_pk_mul_f32 v[122:123], v[122:123], v[158:159] op_sel_hi:[1,0]
	v_pk_mul_f32 v[124:125], v[124:125], v[158:159] op_sel_hi:[1,0]
	v_pk_mul_f32 v[122:123], v[186:187], v[122:123]
	v_pk_mul_f32 v[124:125], v[188:189], v[124:125]
	global_store_dwordx4 v143, v[122:125], s[98:99] offset:64
	v_pk_mul_f32 v[110:111], v[110:111], v[158:159] op_sel_hi:[1,0]
	v_pk_mul_f32 v[112:113], v[112:113], v[158:159] op_sel_hi:[1,0]
	v_pk_mul_f32 v[110:111], v[190:191], v[110:111]
	v_pk_mul_f32 v[112:113], v[192:193], v[112:113]
	global_store_dwordx4 v143, v[110:113], s[98:99] offset:512
	v_pk_mul_f32 v[106:107], v[106:107], v[158:159] op_sel_hi:[1,0]
	v_pk_mul_f32 v[108:109], v[108:109], v[158:159] op_sel_hi:[1,0]
	v_pk_mul_f32 v[106:107], v[194:195], v[106:107]
	v_pk_mul_f32 v[108:109], v[196:197], v[108:109]
	global_store_dwordx4 v143, v[106:109], s[98:99] offset:576
	v_add_u32_e32 v143, 0x10000, v142
	v_mov_b32_e32 v158, v199
	v_pk_mul_f32 v[118:119], v[118:119], v[158:159] op_sel_hi:[1,0]
	v_pk_mul_f32 v[120:121], v[120:121], v[158:159] op_sel_hi:[1,0]
	v_pk_mul_f32 v[118:119], v[182:183], v[118:119]
	v_pk_mul_f32 v[120:121], v[184:185], v[120:121]
	global_store_dwordx4 v143, v[118:121], s[98:99]
	v_pk_mul_f32 v[114:115], v[114:115], v[158:159] op_sel_hi:[1,0]
	v_pk_mul_f32 v[116:117], v[116:117], v[158:159] op_sel_hi:[1,0]
	v_pk_mul_f32 v[114:115], v[186:187], v[114:115]
	v_pk_mul_f32 v[116:117], v[188:189], v[116:117]
	global_store_dwordx4 v143, v[114:117], s[98:99] offset:64
	v_pk_mul_f32 v[102:103], v[102:103], v[158:159] op_sel_hi:[1,0]
	v_pk_mul_f32 v[104:105], v[104:105], v[158:159] op_sel_hi:[1,0]
	v_pk_mul_f32 v[102:103], v[190:191], v[102:103]
	v_pk_mul_f32 v[104:105], v[192:193], v[104:105]
	global_store_dwordx4 v143, v[102:105], s[98:99] offset:512
	v_pk_mul_f32 v[98:99], v[98:99], v[158:159] op_sel_hi:[1,0]
	v_pk_mul_f32 v[100:101], v[100:101], v[158:159] op_sel_hi:[1,0]
	v_pk_mul_f32 v[98:99], v[194:195], v[98:99]
	v_pk_mul_f32 v[100:101], v[196:197], v[100:101]
	global_store_dwordx4 v143, v[98:101], s[98:99] offset:576
	v_add_u32_e32 v143, 0x20000, v142
	v_mov_b32_e32 v158, v200
	v_pk_mul_f32 v[94:95], v[94:95], v[158:159] op_sel_hi:[1,0]
	v_pk_mul_f32 v[96:97], v[96:97], v[158:159] op_sel_hi:[1,0]
	v_pk_mul_f32 v[94:95], v[182:183], v[94:95]
	v_pk_mul_f32 v[96:97], v[184:185], v[96:97]
	global_store_dwordx4 v143, v[94:97], s[98:99]
	v_pk_mul_f32 v[90:91], v[90:91], v[158:159] op_sel_hi:[1,0]
	v_pk_mul_f32 v[92:93], v[92:93], v[158:159] op_sel_hi:[1,0]
	v_pk_mul_f32 v[90:91], v[186:187], v[90:91]
	v_pk_mul_f32 v[92:93], v[188:189], v[92:93]
	global_store_dwordx4 v143, v[90:93], s[98:99] offset:64
	v_pk_mul_f32 v[78:79], v[78:79], v[158:159] op_sel_hi:[1,0]
	v_pk_mul_f32 v[80:81], v[80:81], v[158:159] op_sel_hi:[1,0]
	v_pk_mul_f32 v[78:79], v[190:191], v[78:79]
	v_pk_mul_f32 v[80:81], v[192:193], v[80:81]
	global_store_dwordx4 v143, v[78:81], s[98:99] offset:512
	v_pk_mul_f32 v[74:75], v[74:75], v[158:159] op_sel_hi:[1,0]
	v_pk_mul_f32 v[76:77], v[76:77], v[158:159] op_sel_hi:[1,0]
	v_pk_mul_f32 v[74:75], v[194:195], v[74:75]
	v_pk_mul_f32 v[76:77], v[196:197], v[76:77]
; #define GAS __attribute__((address_space(1)))
; __device__ __forceinline__ void rms_row2_f32(float* xrow0, const float* g, int lane, bool second_valid) {
;     const int hl = lane & 31, hw = lane >> 5;
;     if (hw && !second_valid) return;
;     GAS f32x4* xr = (GAS f32x4*)(xrow0 + (size_t)hw * DM) + hl; const GAS f32x4* gr = (const GAS f32x4*)g + hl;
;     f32x4 v[8]; float s = 0.f;
; #pragma unroll
;     for (int j = 0; j < 8; ++j) { v[j] = NTL(xr + 32 * j); s += (v[j].x * v[j].x + v[j].y * v[j].y) + (v[j].z * v[j].z + v[j].w * v[j].w); }
; #pragma unroll
;     for (int o = 1; o < 32; o <<= 1) s += __shfl_xor(s, o);
;     const float rstd = 1.f / sqrtf(s * (1.f / DM) + EPS);
; #pragma unroll
;     for (int j = 0; j < 8; ++j) { const f32x4 gg = gr[32 * j]; xr[32 * j] = v[j] * rstd * gg; }
	global_store_dwordx4 v143, v[74:77], s[98:99] offset:576
	v_add_u32_e32 v143, 0x30000, v142
	v_mov_b32_e32 v158, v201
	v_pk_mul_f32 v[86:87], v[86:87], v[158:159] op_sel_hi:[1,0]
	v_pk_mul_f32 v[88:89], v[88:89], v[158:159] op_sel_hi:[1,0]
	v_pk_mul_f32 v[86:87], v[182:183], v[86:87]
	v_pk_mul_f32 v[88:89], v[184:185], v[88:89]
	global_store_dwordx4 v143, v[86:89], s[98:99]
	v_pk_mul_f32 v[82:83], v[82:83], v[158:159] op_sel_hi:[1,0]
	v_pk_mul_f32 v[84:85], v[84:85], v[158:159] op_sel_hi:[1,0]
	v_pk_mul_f32 v[82:83], v[186:187], v[82:83]
	v_pk_mul_f32 v[84:85], v[188:189], v[84:85]
	global_store_dwordx4 v143, v[82:85], s[98:99] offset:64
	v_pk_mul_f32 v[70:71], v[70:71], v[158:159] op_sel_hi:[1,0]
	v_pk_mul_f32 v[72:73], v[72:73], v[158:159] op_sel_hi:[1,0]
	v_pk_mul_f32 v[70:71], v[190:191], v[70:71]
	v_pk_mul_f32 v[72:73], v[192:193], v[72:73]
	global_store_dwordx4 v143, v[70:73], s[98:99] offset:512
	v_pk_mul_f32 v[66:67], v[66:67], v[158:159] op_sel_hi:[1,0]
	v_pk_mul_f32 v[68:69], v[68:69], v[158:159] op_sel_hi:[1,0]
	v_pk_mul_f32 v[66:67], v[194:195], v[66:67]
	v_pk_mul_f32 v[68:69], v[196:197], v[68:69]
	global_store_dwordx4 v143, v[66:69], s[98:99] offset:576
	v_add_u32_e32 v143, 0x80000, v142
	v_mov_b32_e32 v158, v202
	v_pk_mul_f32 v[62:63], v[62:63], v[158:159] op_sel_hi:[1,0]
	v_pk_mul_f32 v[64:65], v[64:65], v[158:159] op_sel_hi:[1,0]
	v_pk_mul_f32 v[62:63], v[182:183], v[62:63]
	v_pk_mul_f32 v[64:65], v[184:185], v[64:65]
	global_store_dwordx4 v143, v[62:65], s[98:99]
	v_pk_mul_f32 v[58:59], v[58:59], v[158:159] op_sel_hi:[1,0]
	v_pk_mul_f32 v[60:61], v[60:61], v[158:159] op_sel_hi:[1,0]
	v_pk_mul_f32 v[58:59], v[186:187], v[58:59]
	v_pk_mul_f32 v[60:61], v[188:189], v[60:61]
	global_store_dwordx4 v143, v[58:61], s[98:99] offset:64
	v_pk_mul_f32 v[46:47], v[46:47], v[158:159] op_sel_hi:[1,0]
	v_pk_mul_f32 v[48:49], v[48:49], v[158:159] op_sel_hi:[1,0]
	v_pk_mul_f32 v[46:47], v[190:191], v[46:47]
	v_pk_mul_f32 v[48:49], v[192:193], v[48:49]
	global_store_dwordx4 v143, v[46:49], s[98:99] offset:512
	v_pk_mul_f32 v[42:43], v[42:43], v[158:159] op_sel_hi:[1,0]
	v_pk_mul_f32 v[44:45], v[44:45], v[158:159] op_sel_hi:[1,0]
	v_pk_mul_f32 v[42:43], v[194:195], v[42:43]
	v_pk_mul_f32 v[44:45], v[196:197], v[44:45]
	global_store_dwordx4 v143, v[42:45], s[98:99] offset:576
	v_add_u32_e32 v143, 0x90000, v142
	v_mov_b32_e32 v158, v203
	v_pk_mul_f32 v[54:55], v[54:55], v[158:159] op_sel_hi:[1,0]
	v_pk_mul_f32 v[56:57], v[56:57], v[158:159] op_sel_hi:[1,0]
	v_pk_mul_f32 v[54:55], v[182:183], v[54:55]
	v_pk_mul_f32 v[56:57], v[184:185], v[56:57]
	global_store_dwordx4 v143, v[54:57], s[98:99]
	v_pk_mul_f32 v[50:51], v[50:51], v[158:159] op_sel_hi:[1,0]
	v_pk_mul_f32 v[52:53], v[52:53], v[158:159] op_sel_hi:[1,0]
	v_pk_mul_f32 v[50:51], v[186:187], v[50:51]
	v_pk_mul_f32 v[52:53], v[188:189], v[52:53]
	global_store_dwordx4 v143, v[50:53], s[98:99] offset:64
	v_pk_mul_f32 v[38:39], v[38:39], v[158:159] op_sel_hi:[1,0]
	v_pk_mul_f32 v[40:41], v[40:41], v[158:159] op_sel_hi:[1,0]
	v_pk_mul_f32 v[38:39], v[190:191], v[38:39]
	v_pk_mul_f32 v[40:41], v[192:193], v[40:41]
	global_store_dwordx4 v143, v[38:41], s[98:99] offset:512
	v_pk_mul_f32 v[34:35], v[34:35], v[158:159] op_sel_hi:[1,0]
	v_pk_mul_f32 v[36:37], v[36:37], v[158:159] op_sel_hi:[1,0]
	v_pk_mul_f32 v[34:35], v[194:195], v[34:35]
	v_pk_mul_f32 v[36:37], v[196:197], v[36:37]
	global_store_dwordx4 v143, v[34:37], s[98:99] offset:576
	v_add_u32_e32 v143, 0xa0000, v142
	v_mov_b32_e32 v158, v204
	v_pk_mul_f32 v[30:31], v[30:31], v[158:159] op_sel_hi:[1,0]
	v_pk_mul_f32 v[32:33], v[32:33], v[158:159] op_sel_hi:[1,0]
	v_pk_mul_f32 v[30:31], v[182:183], v[30:31]
	v_pk_mul_f32 v[32:33], v[184:185], v[32:33]
	global_store_dwordx4 v143, v[30:33], s[98:99]
	v_pk_mul_f32 v[26:27], v[26:27], v[158:159] op_sel_hi:[1,0]
	v_pk_mul_f32 v[28:29], v[28:29], v[158:159] op_sel_hi:[1,0]
	v_pk_mul_f32 v[26:27], v[186:187], v[26:27]
	v_pk_mul_f32 v[28:29], v[188:189], v[28:29]
	global_store_dwordx4 v143, v[26:29], s[98:99] offset:64
	v_pk_mul_f32 v[18:19], v[18:19], v[158:159] op_sel_hi:[1,0]
	v_pk_mul_f32 v[20:21], v[20:21], v[158:159] op_sel_hi:[1,0]
	v_pk_mul_f32 v[18:19], v[190:191], v[18:19]
	v_pk_mul_f32 v[20:21], v[192:193], v[20:21]
	global_store_dwordx4 v143, v[18:21], s[98:99] offset:512
	v_pk_mul_f32 v[10:11], v[10:11], v[158:159] op_sel_hi:[1,0]
	v_pk_mul_f32 v[12:13], v[12:13], v[158:159] op_sel_hi:[1,0]
	v_pk_mul_f32 v[10:11], v[194:195], v[10:11]
	v_pk_mul_f32 v[12:13], v[196:197], v[12:13]
	global_store_dwordx4 v143, v[10:13], s[98:99] offset:576
	v_add_u32_e32 v143, 0xb0000, v142
	v_mov_b32_e32 v158, v205
	v_pk_mul_f32 v[22:23], v[22:23], v[158:159] op_sel_hi:[1,0]
	v_pk_mul_f32 v[24:25], v[24:25], v[158:159] op_sel_hi:[1,0]
	v_pk_mul_f32 v[22:23], v[182:183], v[22:23]
	v_pk_mul_f32 v[24:25], v[184:185], v[24:25]
	global_store_dwordx4 v143, v[22:25], s[98:99]
	v_pk_mul_f32 v[14:15], v[14:15], v[158:159] op_sel_hi:[1,0]
	v_pk_mul_f32 v[16:17], v[16:17], v[158:159] op_sel_hi:[1,0]
	v_pk_mul_f32 v[14:15], v[186:187], v[14:15]
	v_pk_mul_f32 v[16:17], v[188:189], v[16:17]
	global_store_dwordx4 v143, v[14:17], s[98:99] offset:64
	v_pk_mul_f32 v[6:7], v[6:7], v[158:159] op_sel_hi:[1,0]
	v_pk_mul_f32 v[8:9], v[8:9], v[158:159] op_sel_hi:[1,0]
	v_pk_mul_f32 v[6:7], v[190:191], v[6:7]
	v_pk_mul_f32 v[8:9], v[192:193], v[8:9]
	global_store_dwordx4 v143, v[6:9], s[98:99] offset:512
	v_pk_mul_f32 v[2:3], v[2:3], v[158:159] op_sel_hi:[1,0]
	v_pk_mul_f32 v[4:5], v[4:5], v[158:159] op_sel_hi:[1,0]
	v_pk_mul_f32 v[2:3], v[194:195], v[2:3]
	v_pk_mul_f32 v[4:5], v[196:197], v[4:5]
	global_store_dwordx4 v143, v[2:5], s[98:99] offset:576
	s_mov_b64 s[42:43], -1
	s_and_b64 vcc, exec, s[6:7]
	s_cbranch_vccnz .LBB0_1916
	s_andn2_b64 vcc, exec, s[14:15]
	s_cbranch_vccnz .LBB0_1915
	s_barrier
	s_branch .LBB0_1915
